# nsa_fast_paths_packed_f32_ops_split_to_scalar
# baseline (speedup 1.0000x reference)
.Lnsa_fastm:
	v_bfe_i32 v147, v127, 0, 1
	v_bfe_i32 v148, v127, 1, 1
	v_bfe_i32 v149, v127, 2, 1
	v_bfe_i32 v150, v127, 3, 1
	v_bfi_b32 v152, v147, 0, v102
	v_bfi_b32 v153, v148, 0, v102
	v_bfi_b32 v154, v149, 0, v102
	v_bfi_b32 v155, v150, 0, v102
	v_bfe_i32 v147, v127, 4, 1
	v_bfe_i32 v148, v127, 5, 1
	v_bfe_i32 v149, v127, 6, 1
	v_bfe_i32 v150, v127, 7, 1
	v_bfi_b32 v156, v147, 0, v102
	v_bfi_b32 v157, v148, 0, v102
	v_bfi_b32 v158, v149, 0, v102
	v_bfi_b32 v159, v150, 0, v102
	v_bfe_i32 v147, v127, 8, 1
	v_bfe_i32 v148, v127, 9, 1
	v_bfe_i32 v149, v127, 10, 1
	v_bfe_i32 v150, v127, 11, 1
	v_bfi_b32 v160, v147, 0, v102
	v_bfi_b32 v161, v148, 0, v102
	v_bfi_b32 v162, v149, 0, v102
	v_bfi_b32 v163, v150, 0, v102
	v_bfe_i32 v147, v127, 12, 1
	v_bfe_i32 v148, v127, 13, 1
	v_bfe_i32 v149, v127, 14, 1
	v_bfe_i32 v150, v127, 15, 1
	v_bfi_b32 v164, v147, 0, v102
	v_bfi_b32 v165, v148, 0, v102
	v_bfi_b32 v166, v149, 0, v102
	v_bfi_b32 v167, v150, 0, v102
	s_cmp_lg_u32 s63, 0
	s_cbranch_scc1 .Lnsa_fastm1
	ds_read_b128 v[176:179], v175
	ds_read_b128 v[180:183], v211
	ds_read_b128 v[184:187], v228
	ds_read_b128 v[188:191], v229
	ds_read_b128 v[192:195], v175 offset:64
	ds_read_b128 v[196:199], v211 offset:64
	ds_read_b128 v[200:203], v228 offset:64
	ds_read_b128 v[204:207], v229 offset:64
	ds_read_b128 v[212:215], v231 offset:38912
	ds_read_b128 v[216:219], v231 offset:41216
	ds_read_b128 v[220:223], v231 offset:43520
	ds_read_b128 v[224:227], v252 offset:38912
	ds_read_b128 v[232:235], v231 offset:38976
	ds_read_b128 v[236:239], v231 offset:41280
	s_waitcnt lgkmcnt(10)
	v_mfma_f32_16x16x32_bf16 v[52:55], v[176:179], v[4:7], v[152:155]
	v_mfma_f32_16x16x32_bf16 v[48:51], v[180:183], v[4:7], v[156:159]
	ds_read_b128 v[240:243], v231 offset:43584
	v_mfma_f32_16x16x32_bf16 v[44:47], v[184:187], v[4:7], v[160:163]
	ds_read_b128 v[244:247], v252 offset:38976
	v_mfma_f32_16x16x32_bf16 v[40:43], v[188:191], v[4:7], v[164:167]
	s_waitcnt lgkmcnt(8)
	v_mfma_f32_16x16x32_bf16 v[52:55], v[192:195], v[0:3], v[52:55]
	v_mfma_f32_16x16x32_bf16 v[48:51], v[196:199], v[0:3], v[48:51]
	v_mfma_f32_16x16x32_bf16 v[44:47], v[200:203], v[0:3], v[44:47]
	v_mfma_f32_16x16x32_bf16 v[40:43], v[204:207], v[0:3], v[40:43]
	s_nop 4
	v_max3_f32 v90, v52, v53, v54
	v_max3_f32 v90, v90, v55, v48
	v_max3_f32 v90, v90, v49, v50
	v_max3_f32 v90, v90, v51, v44
	v_max3_f32 v90, v90, v45, v46
	v_max3_f32 v90, v90, v47, v40
	v_max3_f32 v90, v90, v41, v42
	v_max_f32_e32 v90, v90, v43
	v_mov_b32_e32 v124, v90
	s_nop 1
	v_permlane16_swap_b32_e32 v124, v90
	v_max_f32_e32 v90, v90, v124
	v_mov_b32_e32 v124, v90
	s_nop 1
	v_permlane32_swap_b32_e32 v124, v90
	v_max3_f32 v127, v122, v90, v124
	v_sub_f32_e32 v90, v122, v127
	v_exp_f32_e32 v90, v90
	v_cmp_gt_f32_e32 vcc, v127, v122
	s_cbranch_vccz .Lnsa_fastm_norescale
	v_mul_f32_e32 v38, v90, v38
	v_mul_f32_e32 v39, v90, v39
	v_mul_f32_e32 v36, v90, v36
	v_mul_f32_e32 v37, v90, v37
	v_mul_f32_e32 v34, v90, v34
	v_mul_f32_e32 v35, v90, v35
	v_mul_f32_e32 v32, v90, v32
	v_mul_f32_e32 v33, v90, v33
	v_mul_f32_e32 v30, v90, v30
	v_mul_f32_e32 v31, v90, v31
	v_mul_f32_e32 v28, v90, v28
	v_mul_f32_e32 v29, v90, v29
	v_mul_f32_e32 v26, v90, v26
	v_mul_f32_e32 v27, v90, v27
	v_mul_f32_e32 v24, v90, v24
	v_mul_f32_e32 v25, v90, v25
.Lnsa_fastm_norescale:
	v_sub_f32_e32 v52, v52, v127
	v_sub_f32_e32 v53, v53, v127
	v_sub_f32_e32 v54, v54, v127
	v_sub_f32_e32 v55, v55, v127
	v_sub_f32_e32 v48, v48, v127
	v_sub_f32_e32 v49, v49, v127
	v_sub_f32_e32 v50, v50, v127
	v_sub_f32_e32 v51, v51, v127
	v_exp_f32_e32 v128, v52
	v_exp_f32_e32 v129, v53
	v_exp_f32_e32 v130, v54
	v_exp_f32_e32 v131, v55
	v_sub_f32_e32 v44, v44, v127
	v_sub_f32_e32 v45, v45, v127
	v_sub_f32_e32 v46, v46, v127
	v_sub_f32_e32 v47, v47, v127
	v_exp_f32_e32 v132, v48
	v_exp_f32_e32 v133, v49
	v_exp_f32_e32 v134, v50
	v_exp_f32_e32 v135, v51
	v_sub_f32_e32 v40, v40, v127
	v_sub_f32_e32 v41, v41, v127
	v_sub_f32_e32 v42, v42, v127
	v_sub_f32_e32 v43, v43, v127
	v_exp_f32_e32 v136, v44
	v_exp_f32_e32 v137, v45
	v_exp_f32_e32 v138, v46
	v_exp_f32_e32 v139, v47
	v_exp_f32_e32 v140, v40
	v_exp_f32_e32 v141, v41
	v_exp_f32_e32 v142, v42
	v_exp_f32_e32 v143, v43
	v_cvt_pk_bf16_f32 v248, v128, v129
	v_cvt_pk_bf16_f32 v249, v130, v131
	v_cvt_pk_bf16_f32 v250, v132, v133
	v_cvt_pk_bf16_f32 v251, v134, v135
	v_cvt_pk_bf16_f32 v52, v136, v137
	v_cvt_pk_bf16_f32 v53, v138, v139
	v_cvt_pk_bf16_f32 v54, v140, v141
	v_cvt_pk_bf16_f32 v55, v142, v143
	s_waitcnt lgkmcnt(4)
	v_mfma_f32_16x16x32_bf16 v[36:39], v[212:215], v[248:251], v[36:39]
	v_mfma_f32_16x16x32_bf16 v[32:35], v[216:219], v[248:251], v[32:35]
	v_mfma_f32_16x16x32_bf16 v[28:31], v[220:223], v[248:251], v[28:31]
	v_mfma_f32_16x16x32_bf16 v[24:27], v[224:227], v[248:251], v[24:27]
	v_add_f32_e32 v40, v129, v128
	v_add_f32_e32 v40, v130, v40
	v_add_f32_e32 v40, v131, v40
	v_add_f32_e32 v40, v132, v40
	v_add_f32_e32 v40, v133, v40
	s_waitcnt lgkmcnt(0)
	v_mfma_f32_16x16x32_bf16 v[36:39], v[232:235], v[52:55], v[36:39]
	v_add_f32_e32 v40, v134, v40
	v_add_f32_e32 v40, v135, v40
	v_add_f32_e32 v40, v136, v40
	v_mfma_f32_16x16x32_bf16 v[32:35], v[236:239], v[52:55], v[32:35]
	v_add_f32_e32 v40, v137, v40
	v_add_f32_e32 v40, v138, v40
	v_add_f32_e32 v40, v139, v40
	v_mfma_f32_16x16x32_bf16 v[28:31], v[240:243], v[52:55], v[28:31]
	v_add_f32_e32 v40, v140, v40
	v_add_f32_e32 v40, v141, v40
	v_add_f32_e32 v40, v142, v40
	v_mfma_f32_16x16x32_bf16 v[24:27], v[244:247], v[52:55], v[24:27]
	v_add_f32_e32 v40, v143, v40
	v_fmac_f32_e32 v40, v121, v90
	v_mov_b32_e32 v122, v127
	v_mov_b32_e32 v121, v40
	s_branch .Lnsa_fast_done
.Lnsa_fastm1:
	ds_read_b128 v[176:179], v175 offset:9472
	ds_read_b128 v[180:183], v211 offset:9472
	ds_read_b128 v[184:187], v228 offset:9472
	ds_read_b128 v[188:191], v229 offset:9472
	ds_read_b128 v[192:195], v175 offset:9536
	ds_read_b128 v[196:199], v211 offset:9536
	ds_read_b128 v[200:203], v228 offset:9536
	ds_read_b128 v[204:207], v229 offset:9536
	ds_read_b128 v[212:215], v231 offset:48128
	ds_read_b128 v[216:219], v231 offset:50432
	ds_read_b128 v[220:223], v231 offset:52736
	ds_read_b128 v[224:227], v252 offset:48128
	ds_read_b128 v[232:235], v231 offset:48192
	ds_read_b128 v[236:239], v231 offset:50496
	s_waitcnt lgkmcnt(10)
	v_mfma_f32_16x16x32_bf16 v[52:55], v[176:179], v[4:7], v[152:155]
	v_mfma_f32_16x16x32_bf16 v[48:51], v[180:183], v[4:7], v[156:159]
	ds_read_b128 v[240:243], v231 offset:52800
	v_mfma_f32_16x16x32_bf16 v[44:47], v[184:187], v[4:7], v[160:163]
	ds_read_b128 v[244:247], v252 offset:48192
	v_mfma_f32_16x16x32_bf16 v[40:43], v[188:191], v[4:7], v[164:167]
	s_waitcnt lgkmcnt(8)
	v_mfma_f32_16x16x32_bf16 v[52:55], v[192:195], v[0:3], v[52:55]
	v_mfma_f32_16x16x32_bf16 v[48:51], v[196:199], v[0:3], v[48:51]
	v_mfma_f32_16x16x32_bf16 v[44:47], v[200:203], v[0:3], v[44:47]
	v_mfma_f32_16x16x32_bf16 v[40:43], v[204:207], v[0:3], v[40:43]
	s_nop 4
	v_max3_f32 v90, v52, v53, v54
	v_max3_f32 v90, v90, v55, v48
	v_max3_f32 v90, v90, v49, v50
	v_max3_f32 v90, v90, v51, v44
	v_max3_f32 v90, v90, v45, v46
	v_max3_f32 v90, v90, v47, v40
	v_max3_f32 v90, v90, v41, v42
	v_max_f32_e32 v90, v90, v43
	v_mov_b32_e32 v124, v90
	s_nop 1
	v_permlane16_swap_b32_e32 v124, v90
	v_max_f32_e32 v90, v90, v124
	v_mov_b32_e32 v124, v90
	s_nop 1
	v_permlane32_swap_b32_e32 v124, v90
	v_max3_f32 v127, v122, v90, v124
	v_sub_f32_e32 v90, v122, v127
	v_exp_f32_e32 v90, v90
	v_cmp_gt_f32_e32 vcc, v127, v122
	s_cbranch_vccz .Lnsa_fastm1_norescale
	v_mul_f32_e32 v38, v90, v38
	v_mul_f32_e32 v39, v90, v39
	v_mul_f32_e32 v36, v90, v36
	v_mul_f32_e32 v37, v90, v37
	v_mul_f32_e32 v34, v90, v34
	v_mul_f32_e32 v35, v90, v35
	v_mul_f32_e32 v32, v90, v32
	v_mul_f32_e32 v33, v90, v33
	v_mul_f32_e32 v30, v90, v30
	v_mul_f32_e32 v31, v90, v31
	v_mul_f32_e32 v28, v90, v28
	v_mul_f32_e32 v29, v90, v29
	v_mul_f32_e32 v26, v90, v26
	v_mul_f32_e32 v27, v90, v27
	v_mul_f32_e32 v24, v90, v24
	v_mul_f32_e32 v25, v90, v25

.Lnsa_fastq:
	s_cmp_lg_u32 s63, 0
	s_cbranch_scc1 .Lnsa_fastq1
	ds_read_b128 v[176:179], v175
	ds_read_b128 v[180:183], v211
	ds_read_b128 v[184:187], v228
	ds_read_b128 v[188:191], v229
	ds_read_b128 v[192:195], v175 offset:64
	ds_read_b128 v[196:199], v211 offset:64
	ds_read_b128 v[200:203], v228 offset:64
	ds_read_b128 v[204:207], v229 offset:64
	v_cndmask_b32_e64 v168, v102, 0, s[6:7]
	v_mov_b32_e32 v169, v168
	v_mov_b32_e32 v170, v168
	v_mov_b32_e32 v171, v168
	ds_read_b128 v[212:215], v231 offset:38912
	ds_read_b128 v[216:219], v231 offset:41216
	ds_read_b128 v[220:223], v231 offset:43520
	ds_read_b128 v[224:227], v252 offset:38912
	ds_read_b128 v[232:235], v231 offset:38976
	ds_read_b128 v[236:239], v231 offset:41280
	s_waitcnt lgkmcnt(10)
	v_mfma_f32_16x16x32_bf16 v[52:55], v[176:179], v[4:7], v[168:171]
	v_mfma_f32_16x16x32_bf16 v[48:51], v[180:183], v[4:7], v[168:171]
	ds_read_b128 v[240:243], v231 offset:43584
	v_mfma_f32_16x16x32_bf16 v[44:47], v[184:187], v[4:7], v[168:171]
	ds_read_b128 v[244:247], v252 offset:38976
	v_mfma_f32_16x16x32_bf16 v[40:43], v[188:191], v[4:7], v[168:171]
	s_waitcnt lgkmcnt(8)
	v_mfma_f32_16x16x32_bf16 v[52:55], v[192:195], v[0:3], v[52:55]
	v_mfma_f32_16x16x32_bf16 v[48:51], v[196:199], v[0:3], v[48:51]
	v_mfma_f32_16x16x32_bf16 v[44:47], v[200:203], v[0:3], v[44:47]
	v_mfma_f32_16x16x32_bf16 v[40:43], v[204:207], v[0:3], v[40:43]
	s_nop 4
	v_max3_f32 v90, v52, v53, v54
	v_max3_f32 v90, v90, v55, v48
	v_max3_f32 v90, v90, v49, v50
	v_max3_f32 v90, v90, v51, v44
	v_max3_f32 v90, v90, v45, v46
	v_max3_f32 v90, v90, v47, v40
	v_max3_f32 v90, v90, v41, v42
	v_max_f32_e32 v90, v90, v43
	v_mov_b32_e32 v124, v90
	s_nop 1
	v_permlane16_swap_b32_e32 v124, v90
	v_max_f32_e32 v90, v90, v124
	v_mov_b32_e32 v124, v90
	s_nop 1
	v_permlane32_swap_b32_e32 v124, v90
	v_max3_f32 v127, v122, v90, v124
	v_sub_f32_e32 v90, v122, v127
	v_exp_f32_e32 v90, v90
	v_cmp_gt_f32_e32 vcc, v127, v122
	s_cbranch_vccz .Lnsa_fastq_norescale
	v_mul_f32_e32 v38, v90, v38
	v_mul_f32_e32 v39, v90, v39
	v_mul_f32_e32 v36, v90, v36
	v_mul_f32_e32 v37, v90, v37
	v_mul_f32_e32 v34, v90, v34
	v_mul_f32_e32 v35, v90, v35
	v_mul_f32_e32 v32, v90, v32
	v_mul_f32_e32 v33, v90, v33
	v_mul_f32_e32 v30, v90, v30
	v_mul_f32_e32 v31, v90, v31
	v_mul_f32_e32 v28, v90, v28
	v_mul_f32_e32 v29, v90, v29
	v_mul_f32_e32 v26, v90, v26
	v_mul_f32_e32 v27, v90, v27
	v_mul_f32_e32 v24, v90, v24
	v_mul_f32_e32 v25, v90, v25
.Lnsa_fastq_norescale:
	v_sub_f32_e32 v52, v52, v127
	v_sub_f32_e32 v53, v53, v127
	v_sub_f32_e32 v54, v54, v127
	v_sub_f32_e32 v55, v55, v127
	v_sub_f32_e32 v48, v48, v127
	v_sub_f32_e32 v49, v49, v127
	v_sub_f32_e32 v50, v50, v127
	v_sub_f32_e32 v51, v51, v127
	v_exp_f32_e32 v128, v52
	v_exp_f32_e32 v129, v53
	v_exp_f32_e32 v130, v54
	v_exp_f32_e32 v131, v55
	v_sub_f32_e32 v44, v44, v127
	v_sub_f32_e32 v45, v45, v127
	v_sub_f32_e32 v46, v46, v127
	v_sub_f32_e32 v47, v47, v127
	v_exp_f32_e32 v132, v48
	v_exp_f32_e32 v133, v49
	v_exp_f32_e32 v134, v50
	v_exp_f32_e32 v135, v51
	v_sub_f32_e32 v40, v40, v127
	v_sub_f32_e32 v41, v41, v127
	v_sub_f32_e32 v42, v42, v127
	v_sub_f32_e32 v43, v43, v127
	v_exp_f32_e32 v136, v44
	v_exp_f32_e32 v137, v45
	v_exp_f32_e32 v138, v46
	v_exp_f32_e32 v139, v47
	v_exp_f32_e32 v140, v40
	v_exp_f32_e32 v141, v41
	v_exp_f32_e32 v142, v42
	v_exp_f32_e32 v143, v43
	v_cvt_pk_bf16_f32 v248, v128, v129
	v_cvt_pk_bf16_f32 v249, v130, v131
	v_cvt_pk_bf16_f32 v250, v132, v133
	v_cvt_pk_bf16_f32 v251, v134, v135
	v_cvt_pk_bf16_f32 v52, v136, v137
	v_cvt_pk_bf16_f32 v53, v138, v139
	v_cvt_pk_bf16_f32 v54, v140, v141
	v_cvt_pk_bf16_f32 v55, v142, v143
	v_add_f32_e32 v40, v132, v128
	v_add_f32_e32 v41, v133, v129
	v_add_f32_e32 v42, v134, v130
	v_add_f32_e32 v43, v135, v131
	v_add_f32_e32 v40, v136, v40
	v_add_f32_e32 v41, v137, v41
	v_add_f32_e32 v42, v138, v42
	v_add_f32_e32 v43, v139, v43
	v_add_f32_e32 v40, v140, v40
	v_add_f32_e32 v41, v141, v41
	v_add_f32_e32 v42, v142, v42
	v_add_f32_e32 v43, v143, v43
	s_waitcnt lgkmcnt(4)
	v_mfma_f32_16x16x32_bf16 v[36:39], v[212:215], v[248:251], v[36:39]
	v_mfma_f32_16x16x32_bf16 v[32:35], v[216:219], v[248:251], v[32:35]
	v_mfma_f32_16x16x32_bf16 v[28:31], v[220:223], v[248:251], v[28:31]
	v_mfma_f32_16x16x32_bf16 v[24:27], v[224:227], v[248:251], v[24:27]
	s_waitcnt lgkmcnt(0)
	v_mfma_f32_16x16x32_bf16 v[36:39], v[232:235], v[52:55], v[36:39]
	v_add_f32_e32 v40, v40, v41
	v_mfma_f32_16x16x32_bf16 v[32:35], v[236:239], v[52:55], v[32:35]
	v_fmac_f32_e32 v40, v121, v90
	v_mfma_f32_16x16x32_bf16 v[28:31], v[240:243], v[52:55], v[28:31]
	v_add_f32_e32 v42, v42, v43
	v_mfma_f32_16x16x32_bf16 v[24:27], v[244:247], v[52:55], v[24:27]
	v_mov_b32_e32 v122, v127
	v_add_f32_e32 v121, v42, v40
	s_branch .Lnsa_fast_done
.Lnsa_fastq1:
	ds_read_b128 v[176:179], v175 offset:9472
	ds_read_b128 v[180:183], v211 offset:9472
	ds_read_b128 v[184:187], v228 offset:9472
	ds_read_b128 v[188:191], v229 offset:9472
	ds_read_b128 v[192:195], v175 offset:9536
	ds_read_b128 v[196:199], v211 offset:9536
	ds_read_b128 v[200:203], v228 offset:9536
	ds_read_b128 v[204:207], v229 offset:9536
	v_cndmask_b32_e64 v168, v102, 0, s[6:7]
	v_mov_b32_e32 v169, v168
	v_mov_b32_e32 v170, v168
	v_mov_b32_e32 v171, v168
	ds_read_b128 v[212:215], v231 offset:48128
	ds_read_b128 v[216:219], v231 offset:50432
	ds_read_b128 v[220:223], v231 offset:52736
	ds_read_b128 v[224:227], v252 offset:48128
	ds_read_b128 v[232:235], v231 offset:48192
	ds_read_b128 v[236:239], v231 offset:50496
	s_waitcnt lgkmcnt(10)
	v_mfma_f32_16x16x32_bf16 v[52:55], v[176:179], v[4:7], v[168:171]
	v_mfma_f32_16x16x32_bf16 v[48:51], v[180:183], v[4:7], v[168:171]
	ds_read_b128 v[240:243], v231 offset:52800
	v_mfma_f32_16x16x32_bf16 v[44:47], v[184:187], v[4:7], v[168:171]
	ds_read_b128 v[244:247], v252 offset:48192
	v_mfma_f32_16x16x32_bf16 v[40:43], v[188:191], v[4:7], v[168:171]
	s_waitcnt lgkmcnt(8)
	v_mfma_f32_16x16x32_bf16 v[52:55], v[192:195], v[0:3], v[52:55]
	v_mfma_f32_16x16x32_bf16 v[48:51], v[196:199], v[0:3], v[48:51]
	v_mfma_f32_16x16x32_bf16 v[44:47], v[200:203], v[0:3], v[44:47]
	v_mfma_f32_16x16x32_bf16 v[40:43], v[204:207], v[0:3], v[40:43]
	s_nop 4
	v_max3_f32 v90, v52, v53, v54
	v_max3_f32 v90, v90, v55, v48
	v_max3_f32 v90, v90, v49, v50
	v_max3_f32 v90, v90, v51, v44
	v_max3_f32 v90, v90, v45, v46
	v_max3_f32 v90, v90, v47, v40
	v_max3_f32 v90, v90, v41, v42
	v_max_f32_e32 v90, v90, v43
	v_mov_b32_e32 v124, v90
	s_nop 1
	v_permlane16_swap_b32_e32 v124, v90
	v_max_f32_e32 v90, v90, v124
	v_mov_b32_e32 v124, v90
	s_nop 1
	v_permlane32_swap_b32_e32 v124, v90
	v_max3_f32 v127, v122, v90, v124
	v_sub_f32_e32 v90, v122, v127
	v_exp_f32_e32 v90, v90
	v_cmp_gt_f32_e32 vcc, v127, v122
	s_cbranch_vccz .Lnsa_fastq1_norescale
	v_mul_f32_e32 v38, v90, v38
	v_mul_f32_e32 v39, v90, v39
	v_mul_f32_e32 v36, v90, v36
	v_mul_f32_e32 v37, v90, v37
	v_mul_f32_e32 v34, v90, v34
	v_mul_f32_e32 v35, v90, v35
	v_mul_f32_e32 v32, v90, v32
	v_mul_f32_e32 v33, v90, v33
	v_mul_f32_e32 v30, v90, v30
	v_mul_f32_e32 v31, v90, v31
	v_mul_f32_e32 v28, v90, v28
	v_mul_f32_e32 v29, v90, v29
	v_mul_f32_e32 v26, v90, v26
	v_mul_f32_e32 v27, v90, v27
	v_mul_f32_e32 v24, v90, v24
	v_mul_f32_e32 v25, v90, v25

.Lnsa_fast:
	ds_read_b128 v[176:179], v126
	ds_read_b128 v[180:183], v125
	ds_read_b128 v[184:187], v124
	ds_read_b128 v[188:191], v90
	ds_read_b128 v[192:195], v126 offset:64
	ds_read_b128 v[196:199], v125 offset:64
	ds_read_b128 v[200:203], v124 offset:64
	ds_read_b128 v[204:207], v90 offset:64
	v_add_u32_e32 v172, v123, v119
	v_add_u32_e32 v173, v123, v120
	v_cndmask_b32_e64 v168, v102, 0, s[6:7]
	v_mov_b32_e32 v169, v168
	v_mov_b32_e32 v170, v168
	v_mov_b32_e32 v171, v168
	ds_read_b128 v[212:215], v172 offset:38912
	ds_read_b128 v[216:219], v172 offset:41216
	ds_read_b128 v[220:223], v172 offset:43520
	ds_read_b128 v[224:227], v173 offset:38912
	ds_read_b128 v[232:235], v172 offset:38976
	ds_read_b128 v[236:239], v172 offset:41280
	s_waitcnt lgkmcnt(13)
	v_mfma_f32_16x16x32_bf16 v[52:55], v[176:179], v[4:7], v[168:171]
	ds_read_b128 v[240:243], v172 offset:43584
	s_waitcnt lgkmcnt(13)
	v_mfma_f32_16x16x32_bf16 v[48:51], v[180:183], v[4:7], v[168:171]
	ds_read_b128 v[244:247], v173 offset:38976
	s_waitcnt lgkmcnt(13)
	v_mfma_f32_16x16x32_bf16 v[44:47], v[184:187], v[4:7], v[168:171]
	s_waitcnt lgkmcnt(12)
	v_mfma_f32_16x16x32_bf16 v[40:43], v[188:191], v[4:7], v[168:171]
	s_waitcnt lgkmcnt(11)
	v_mfma_f32_16x16x32_bf16 v[52:55], v[192:195], v[0:3], v[52:55]
	s_waitcnt lgkmcnt(10)
	v_mfma_f32_16x16x32_bf16 v[48:51], v[196:199], v[0:3], v[48:51]
	s_waitcnt lgkmcnt(9)
	v_mfma_f32_16x16x32_bf16 v[44:47], v[200:203], v[0:3], v[44:47]
	s_waitcnt lgkmcnt(8)
	v_mfma_f32_16x16x32_bf16 v[40:43], v[204:207], v[0:3], v[40:43]
	s_nop 4
	v_max3_f32 v90, v52, v53, v54
	v_max3_f32 v90, v90, v55, v48
	v_max3_f32 v90, v90, v49, v50
	v_max3_f32 v90, v90, v51, v44
	v_max3_f32 v90, v90, v45, v46
	v_max3_f32 v90, v90, v47, v40
	v_max3_f32 v90, v90, v41, v42
	v_max_f32_e32 v90, v90, v43
	v_mov_b32_e32 v124, v90
	s_nop 1
	v_permlane16_swap_b32_e32 v124, v90
	v_max_f32_e32 v90, v90, v124
	v_mov_b32_e32 v124, v90
	s_nop 1
	v_permlane32_swap_b32_e32 v124, v90
	v_max3_f32 v127, v122, v90, v124
	v_sub_f32_e32 v90, v122, v127
	v_exp_f32_e32 v90, v90
	v_cmp_gt_f32_e32 vcc, v127, v122
	s_cbranch_vccz .Lnsa_fast_norescale
	v_mul_f32_e32 v38, v90, v38
	v_mul_f32_e32 v39, v90, v39
	v_mul_f32_e32 v36, v90, v36
	v_mul_f32_e32 v37, v90, v37
	v_mul_f32_e32 v34, v90, v34
	v_mul_f32_e32 v35, v90, v35
	v_mul_f32_e32 v32, v90, v32
	v_mul_f32_e32 v33, v90, v33
	v_mul_f32_e32 v30, v90, v30
	v_mul_f32_e32 v31, v90, v31
	v_mul_f32_e32 v28, v90, v28
	v_mul_f32_e32 v29, v90, v29
	v_mul_f32_e32 v26, v90, v26
	v_mul_f32_e32 v27, v90, v27
	v_mul_f32_e32 v24, v90, v24
	v_mul_f32_e32 v25, v90, v25
